# GQA attention loop: K/V prefetch staged through dead VGPRs v200-207 and issued one iteration earlier
# baseline (speedup 1.0000x reference)
.LBB0_1197:
	s_lshl_b32 s5, s0, 8
	s_lshl_b32 s4, s1, 12
	s_and_b32 s5, s5, 0xf00
	s_or_b32 s4, s4, s5
	s_addk_i32 s4, 0x2000
	s_and_b32 s3, s3, 1
	s_mul_hi_i32 s5, s4, 0x1600
	s_mulk_i32 s4, 0x1600
	v_readlane_b32 s6, v254, 62
	v_readlane_b32 s7, v254, 63
	s_add_u32 s6, s6, s4
	s_addc_u32 s7, s7, s5
	s_lshl_b32 s0, s0, 2
	s_lshl_b32 s4, s3, 8
	s_andn2_b32 s0, s0, 63
	s_add_i32 s26, s4, s0
	s_lshl_b64 s[4:5], s[26:27], 1
	s_add_u32 s0, s6, s4
	s_addc_u32 s4, s7, s5
	s_add_u32 s6, s0, 0x1000
	s_addc_u32 s7, s4, 0
	s_mul_i32 s4, s1, 0x110000
	v_readlane_b32 s8, v255, 35
	s_mul_hi_i32 s0, s1, 0x110000
	v_readlane_b32 s9, v255, 36
	s_add_u32 s4, s8, s4
	s_addc_u32 s0, s9, s0
	s_lshl_b32 s5, s3, 6
	s_lshl_b32 s3, s3, 7
	s_add_u32 s8, s4, s3
	s_addc_u32 s9, s0, 0
	s_lshl_b32 s0, s1, 7
	s_or_b32 s0, s0, s5
	s_mul_i32 s4, s0, 0x2200
	v_readlane_b32 s10, v255, 39
	v_mov_b32_e32 v20, v128
	s_mul_hi_i32 s5, s0, 0x2200
	v_readlane_b32 s11, v255, 40
	s_add_u32 s10, s10, s4
	s_addc_u32 s11, s11, s5
	v_readfirstlane_b32 s0, v20
	s_ashr_i32 s0, s0, 1
	v_bfe_u32 v21, v20, 5, 1
	v_mov_b32_e32 v0, s0
	s_movk_i32 s0, 0xffe0
	v_bfi_b32 v2, s0, v0, v20
	v_mov_b64_e32 v[0:1], s[6:7]
	s_movk_i32 s0, 0x1600
	v_ashrrev_i32_e32 v16, 3, v20
	v_mad_i64_i32 v[88:89], s[6:7], v2, s0, v[0:1]
	v_lshlrev_b32_e32 v130, 4, v21
	v_lshlrev_b32_e32 v22, 3, v20
	v_ashrrev_i32_e32 v17, 31, v16
	v_lshl_add_u64 v[0:1], v[88:89], 0, v[130:131]
	v_and_b32_e32 v23, 56, v22
	v_lshlrev_b64 v[18:19], 8, v[16:17]
	global_load_dwordx4 v[76:79], v[0:1], off
	global_load_dwordx4 v[72:75], v[0:1], off offset:32
	global_load_dwordx4 v[68:71], v[0:1], off offset:64
	global_load_dwordx4 v[64:67], v[0:1], off offset:96
	v_lshl_add_u64 v[0:1], s[8:9], 0, v[18:19]
	v_lshlrev_b32_e32 v2, 1, v23
	v_mov_b32_e32 v3, v131
	v_mov_b64_e32 v[4:5], s[10:11]
	s_movk_i32 s8, 0x2200
	v_lshl_add_u64 v[0:1], v[0:1], 0, v[2:3]
	v_mad_i64_i32 v[4:5], s[6:7], v16, s8, v[4:5]
	s_waitcnt vmcnt(63) expcnt(7) lgkmcnt(15)
	s_barrier
	v_lshl_add_u64 v[2:3], v[4:5], 0, v[2:3]
	global_load_dwordx4 v[8:11], v[0:1], off
	global_load_dwordx4 v[12:15], v[2:3], off
	s_movk_i32 s6, 0x48
	v_and_b32_e32 v17, 31, v20
	v_lshlrev_b32_e32 v90, 3, v21
	v_mul_lo_u32 v21, v16, s6
	v_and_b32_e32 v22, 48, v22
	v_lshlrev_b32_e32 v24, 2, v20
	v_lshlrev_b32_e32 v20, 4, v20
	v_mul_u32_u24_e32 v25, 0x48, v17
	v_mul_u32_u24_e32 v93, 0x90, v17
	v_add_u32_e32 v17, v21, v22
	v_mad_i64_i32 v[18:19], s[6:7], s1, v180, v[18:19]
	v_and_b32_e32 v20, 0x70, v20
	v_and_or_b32 v17, v24, 4, v17
	v_readlane_b32 s6, v253, 16
	v_lshlrev_b32_e32 v100, 1, v17
	v_or3_b32 v18, v18, s3, v20
	v_readlane_b32 s7, v253, 17
	v_add_u32_e32 v17, 0, v100
	v_add_lshl_u32 v98, v21, v23, 1
	v_lshl_add_u64 v[94:95], s[6:7], 0, v[18:19]
	v_mov_b64_e32 v[18:19], s[4:5]
	v_add_u32_e32 v22, 0x2000, v17
	v_mad_i64_i32 v[16:17], s[4:5], v16, s8, v[18:19]
	v_add_u32_e32 v21, 0, v98
	v_readlane_b32 s4, v253, 12
	v_or_b32_e32 v16, v16, v20
	v_readlane_b32 s5, v253, 13
	v_mov_b32_e32 v0, v131
	v_mov_b32_e32 v1, v131
	v_mov_b32_e32 v2, v131
	v_mov_b32_e32 v3, v131
	v_mov_b32_e32 v4, v131
	v_mov_b32_e32 v5, v131
	v_mov_b32_e32 v6, v131
	s_waitcnt vmcnt(1)
	ds_write_b128 v21, v[8:11]
	s_waitcnt vmcnt(0)
	ds_write2_b64 v22, v[12:13], v[14:15] offset0:128 offset1:130
	v_mov_b32_e32 v14, v131
	v_mov_b32_e32 v15, v131
	v_mov_b32_e32 v7, v131
	v_add_lshl_u32 v99, v90, v25, 1
	v_lshl_add_u64 v[96:97], s[4:5], 0, v[16:17]
	v_mov_b32_e32 v8, v131
	v_mov_b32_e32 v9, v131
	v_mov_b32_e32 v10, v131
	v_mov_b32_e32 v11, v131
	v_mov_b32_e32 v12, v131
	v_mov_b32_e32 v13, v131
	v_mov_b64_e32 v[30:31], v[14:15]
	s_mov_b32 s0, 0
	v_mov_b32_e32 v91, 0
	v_mov_b32_e32 v92, 0xff800000
	v_mov_b64_e32 v[28:29], v[12:13]
	v_mov_b64_e32 v[26:27], v[10:11]
	v_mov_b64_e32 v[24:25], v[8:9]
	v_mov_b64_e32 v[22:23], v[6:7]
	v_mov_b64_e32 v[20:21], v[4:5]
	v_mov_b64_e32 v[18:19], v[2:3]
	v_mov_b64_e32 v[16:17], v[0:1]
	global_load_dwordx4 v[200:203], v[94:95], off
	global_load_dwordx4 v[204:207], v[96:97], off
	s_waitcnt lgkmcnt(0)
	s_barrier
	s_branch .LBB0_1199
.LBB0_1198:
	v_pk_add_f32 v[48:49], v[48:49], v[92:93] op_sel_hi:[1,0] neg_lo:[0,1] neg_hi:[0,1]
	v_pk_add_f32 v[32:33], v[32:33], v[92:93] op_sel_hi:[1,0] neg_lo:[0,1] neg_hi:[0,1]
	v_exp_f32_e32 v102, v48
	v_exp_f32_e32 v103, v49
	v_exp_f32_e32 v32, v32
	v_exp_f32_e32 v33, v33
	v_pk_add_f32 v[50:51], v[50:51], v[92:93] op_sel_hi:[1,0] neg_lo:[0,1] neg_hi:[0,1]
	v_pk_add_f32 v[34:35], v[34:35], v[92:93] op_sel_hi:[1,0] neg_lo:[0,1] neg_hi:[0,1]
	v_exp_f32_e32 v104, v50
	v_exp_f32_e32 v105, v51
	v_exp_f32_e32 v34, v34
	v_exp_f32_e32 v35, v35
	v_pk_add_f32 v[50:51], v[52:53], v[92:93] op_sel_hi:[1,0] neg_lo:[0,1] neg_hi:[0,1]
	v_pk_add_f32 v[48:49], v[102:103], 0 op_sel_hi:[1,0]
	v_pk_add_f32 v[36:37], v[36:37], v[92:93] op_sel_hi:[1,0] neg_lo:[0,1] neg_hi:[0,1]
	v_exp_f32_e32 v106, v50
	v_exp_f32_e32 v107, v51
	v_pk_add_f32 v[48:49], v[32:33], v[48:49]
	v_exp_f32_e32 v36, v36
	v_exp_f32_e32 v37, v37
	v_pk_add_f32 v[48:49], v[104:105], v[48:49]
	v_add3_u32 v101, s3, v93, v130
	v_pk_add_f32 v[48:49], v[34:35], v[48:49]
	v_pk_add_f32 v[58:59], v[58:59], v[92:93] op_sel_hi:[1,0] neg_lo:[0,1] neg_hi:[0,1]
	v_pk_add_f32 v[48:49], v[106:107], v[48:49]
	v_pk_add_f32 v[38:39], v[38:39], v[92:93] op_sel_hi:[1,0] neg_lo:[0,1] neg_hi:[0,1]
	v_pk_add_f32 v[52:53], v[36:37], v[48:49]
	v_pk_add_f32 v[48:49], v[54:55], v[92:93] op_sel_hi:[1,0] neg_lo:[0,1] neg_hi:[0,1]
	v_pk_add_f32 v[54:55], v[56:57], v[92:93] op_sel_hi:[1,0] neg_lo:[0,1] neg_hi:[0,1]
	v_exp_f32_e32 v108, v48
	v_exp_f32_e32 v109, v49
	ds_read_b128 v[48:51], v101 offset:9216
	v_exp_f32_e32 v110, v54
	v_exp_f32_e32 v111, v55
	v_cvt_pk_bf16_f32 v54, v102, v103
	v_cvt_pk_bf16_f32 v55, v104, v105
	ds_read_b128 v[102:105], v101 offset:13824
	v_cvt_pk_bf16_f32 v56, v106, v107
	v_cvt_pk_bf16_f32 v57, v108, v109
	v_pk_add_f32 v[62:63], v[62:63], v[92:93] op_sel_hi:[1,0] neg_lo:[0,1] neg_hi:[0,1]
	v_exp_f32_e32 v38, v38
	s_waitcnt lgkmcnt(1)
	v_mfma_f32_32x32x16_bf16 v[0:15], v[48:51], v[54:57], v[0:15]
	v_exp_f32_e32 v48, v58
	v_exp_f32_e32 v49, v59
	v_pk_add_f32 v[50:51], v[60:61], v[92:93] op_sel_hi:[1,0] neg_lo:[0,1] neg_hi:[0,1]
	ds_read_b128 v[58:61], v101 offset:9248
	v_exp_f32_e32 v39, v39
	v_exp_f32_e32 v50, v50
	v_exp_f32_e32 v51, v51
	s_waitcnt lgkmcnt(1)
	v_mfma_f32_32x32x16_bf16 v[16:31], v[102:105], v[54:57], v[16:31]
	ds_read_b128 v[102:105], v101 offset:13856
	v_exp_f32_e32 v62, v62
	v_exp_f32_e32 v63, v63
	v_pk_add_f32 v[52:53], v[108:109], v[52:53]
	v_cvt_pk_bf16_f32 v54, v110, v111
	v_cvt_pk_bf16_f32 v55, v48, v49
	v_cvt_pk_bf16_f32 v56, v50, v51
	v_cvt_pk_bf16_f32 v57, v62, v63
	v_pk_add_f32 v[52:53], v[38:39], v[52:53]
	v_cvt_pk_bf16_f32 v32, v32, v33
	v_cvt_pk_bf16_f32 v33, v34, v35
	v_cvt_pk_bf16_f32 v34, v36, v37
	v_cvt_pk_bf16_f32 v35, v38, v39
	ds_read_b128 v[36:39], v101 offset:13888
	s_waitcnt lgkmcnt(2)
	v_mfma_f32_32x32x16_bf16 v[0:15], v[58:61], v[54:57], v[0:15]
	ds_read_b128 v[58:61], v101 offset:9280
	v_add_f32_e64 v40, v40, -v92
	v_add_f32_e64 v41, v41, -v92
	v_add_f32_e64 v46, v46, -v92
	v_add_f32_e64 v47, v47, -v92
	v_exp_f32_e32 v106, v40
	v_exp_f32_e32 v107, v41
	v_pk_add_f32 v[40:41], v[110:111], v[52:53]
	v_exp_f32_e32 v46, v46
	s_waitcnt lgkmcnt(2)
	v_mfma_f32_32x32x16_bf16 v[16:31], v[102:105], v[54:57], v[16:31]
	v_add_f32_e64 v52, v106, v40
	v_add_f32_e64 v53, v107, v41
	v_add_f32_e64 v40, v42, -v92
	v_add_f32_e64 v41, v43, -v92
	v_exp_f32_e32 v47, v47
	v_exp_f32_e32 v54, v40
	v_exp_f32_e32 v55, v41
	v_pk_add_f32 v[40:41], v[44:45], v[92:93] op_sel_hi:[1,0] neg_lo:[0,1] neg_hi:[0,1]
	s_xor_b32 s1, s1, 1
	v_exp_f32_e32 v44, v40
	v_exp_f32_e32 v45, v41
	ds_read_b128 v[40:43], v101 offset:9312
	s_waitcnt lgkmcnt(2)
	v_mfma_f32_32x32x16_bf16 v[16:31], v[36:39], v[32:35], v[16:31]
	ds_read_b128 v[36:39], v101 offset:13920
	s_mulk_i32 s1, 0x4800
	s_add_i32 s1, s1, 0
	s_add_i32 s0, s0, 1
	s_mov_b64 s[4:5], 0x4000
	v_lshl_add_u64 v[96:97], v[96:97], 0, s[30:31]
	s_cmpk_eq_i32 s0, 0x43
	s_waitcnt lgkmcnt(2)
	v_mfma_f32_32x32x16_bf16 v[0:15], v[58:61], v[32:35], v[0:15]
	v_cvt_pk_bf16_f32 v32, v106, v107
	v_cvt_pk_bf16_f32 v33, v54, v55
	v_cvt_pk_bf16_f32 v34, v44, v45
	v_cvt_pk_bf16_f32 v35, v46, v47
	v_lshl_add_u64 v[94:95], v[94:95], 0, s[4:5]
	s_waitcnt lgkmcnt(1)
	v_mfma_f32_32x32x16_bf16 v[0:15], v[40:43], v[32:35], v[0:15]
	v_add_f32_e64 v40, v48, v52
	v_add_f32_e64 v41, v49, v53
	v_add_f32_e64 v40, v54, v40
	v_add_f32_e64 v41, v55, v41
	v_add_f32_e64 v40, v50, v40
	v_add_f32_e64 v41, v51, v41
	v_pk_add_f32 v[40:41], v[44:45], v[40:41]
	s_waitcnt lgkmcnt(0)
	v_mfma_f32_32x32x16_bf16 v[16:31], v[36:39], v[32:35], v[16:31]
	v_add_f32_e64 v40, v62, v40
	v_add_f32_e64 v41, v63, v41
	v_add_u32_e32 v32, s1, v98
	v_add_f32_e64 v40, v46, v40
	v_add_f32_e64 v41, v47, v41
	v_add_u32_e32 v33, s1, v100
	v_add_f32_e32 v40, v40, v41
	v_add_f32_e32 v91, v91, v40
	s_waitcnt vmcnt(1)
	ds_write_b128 v32, v[200:203]
	v_add_u32_e32 v32, 0x2000, v33
	s_waitcnt vmcnt(0)
	ds_write2_b64 v32, v[204:205], v[206:207] offset0:128 offset1:130
	s_waitcnt lgkmcnt(0)
	s_cbranch_scc1 .Lgqa_last
	global_load_dwordx4 v[200:203], v[94:95], off
	global_load_dwordx4 v[204:207], v[96:97], off
	s_barrier
.LBB0_1199:
	s_and_b32 s1, s0, 1
	s_mul_i32 s3, s1, 0x4800
	s_add_i32 s3, s3, 0
	v_add_u32_e32 v101, s3, v99
	ds_read_b128 v[32:35], v101
	ds_read_b128 v[80:83], v101 offset:32
	s_waitcnt lgkmcnt(1)
	v_mfma_f32_32x32x16_bf16 v[48:63], v[32:35], v[76:79], 0
	ds_read_b128 v[32:35], v101 offset:4608
	ds_read_b128 v[84:87], v101 offset:4640
	s_waitcnt lgkmcnt(1)
	v_mfma_f32_32x32x16_bf16 v[32:47], v[32:35], v[76:79], 0
	v_mfma_f32_32x32x16_bf16 v[48:63], v[80:83], v[72:75], v[48:63]
	ds_read_b128 v[80:83], v101 offset:64
	ds_read_b128 v[102:105], v101 offset:96
	s_waitcnt lgkmcnt(2)
	v_mfma_f32_32x32x16_bf16 v[32:47], v[84:87], v[72:75], v[32:47]
	s_waitcnt lgkmcnt(1)
	v_mfma_f32_32x32x16_bf16 v[48:63], v[80:83], v[68:71], v[48:63]
	ds_read_b128 v[80:83], v101 offset:4672
	ds_read_b128 v[84:87], v101 offset:4704
	s_waitcnt lgkmcnt(1)
	v_mfma_f32_32x32x16_bf16 v[32:47], v[80:83], v[68:71], v[32:47]
	s_waitcnt lgkmcnt(0)
	v_mfma_f32_32x32x16_bf16 v[32:47], v[84:87], v[64:67], v[32:47]
	v_mfma_f32_32x32x16_bf16 v[48:63], v[102:105], v[64:67], v[48:63]
	s_nop 10
	v_max_f32_e32 v101, v32, v32
	s_nop 0
	v_max_f32_e32 v102, v48, v48
	v_max_f32_e32 v101, v102, v101
	v_max3_f32 v101, v101, v49, v33
	v_max3_f32 v101, v101, v50, v34
	v_max3_f32 v101, v101, v51, v35
	v_max3_f32 v101, v101, v52, v36
	v_max3_f32 v101, v101, v53, v37
	v_max3_f32 v101, v101, v54, v38
	v_max3_f32 v101, v101, v55, v39
	v_max3_f32 v101, v101, v56, v40
	v_max3_f32 v101, v101, v57, v41
	v_max3_f32 v101, v101, v58, v42
	v_max3_f32 v101, v101, v59, v43
	v_max3_f32 v101, v101, v60, v44
	v_max3_f32 v101, v101, v61, v45
	v_max3_f32 v101, v101, v62, v46
	v_max3_f32 v101, v101, v63, v47
	v_mov_b32_e32 v102, v101
	s_nop 1
	v_permlane32_swap_b32_e32 v101, v102
	v_max_f32_e32 v102, v102, v102
	v_max_f32_e32 v101, v101, v101
	v_max_f32_e32 v101, v101, v102
	v_add_f32_e32 v102, 0x41000000, v92
	v_cmp_gt_f32_e32 vcc, v101, v102
	s_cbranch_vccz .LBB0_1198
	s_nop 0
	v_cndmask_b32_e32 v101, v92, v101, vcc
	v_sub_f32_e32 v92, v92, v101
	v_exp_f32_e32 v92, v92
	s_nop 0
	v_pk_mul_f32 v[14:15], v[14:15], v[92:93] op_sel_hi:[1,0]
	v_pk_mul_f32 v[12:13], v[12:13], v[92:93] op_sel_hi:[1,0]
	v_pk_mul_f32 v[10:11], v[10:11], v[92:93] op_sel_hi:[1,0]
	v_pk_mul_f32 v[8:9], v[8:9], v[92:93] op_sel_hi:[1,0]
	v_pk_mul_f32 v[6:7], v[6:7], v[92:93] op_sel_hi:[1,0]
	v_pk_mul_f32 v[4:5], v[4:5], v[92:93] op_sel_hi:[1,0]
	v_pk_mul_f32 v[2:3], v[2:3], v[92:93] op_sel_hi:[1,0]
	v_pk_mul_f32 v[0:1], v[0:1], v[92:93] op_sel_hi:[1,0]
	v_pk_mul_f32 v[30:31], v[30:31], v[92:93] op_sel_hi:[1,0]
	v_pk_mul_f32 v[28:29], v[28:29], v[92:93] op_sel_hi:[1,0]
	v_pk_mul_f32 v[26:27], v[26:27], v[92:93] op_sel_hi:[1,0]
	v_pk_mul_f32 v[24:25], v[24:25], v[92:93] op_sel_hi:[1,0]
	v_pk_mul_f32 v[22:23], v[22:23], v[92:93] op_sel_hi:[1,0]
	v_pk_mul_f32 v[20:21], v[20:21], v[92:93] op_sel_hi:[1,0]
	v_pk_mul_f32 v[18:19], v[18:19], v[92:93] op_sel_hi:[1,0]
	v_pk_mul_f32 v[16:17], v[16:17], v[92:93] op_sel_hi:[1,0]
	v_mul_f32_e32 v91, v91, v92
	v_mov_b32_e32 v92, v101
	s_branch .LBB0_1198
.Lgqa_last:
	s_barrier
	s_branch .LBB0_1175
